# O stores deferred past the next unit's first-tile wait and made nt (store acks no longer block the K/V vmcnt waits)
# baseline (speedup 1.0000x reference)
.LBB0_276:
	s_or_b32 s46, s9, s79
	s_and_b32 s98, s46, 7
	s_add_i32 s0, s98, 1
	v_cvt_f32_ubyte0_e32 v0, s0
	s_mov_b32 s0, 0x42fc0000
	v_cmp_lt_f32_e32 vcc, s0, v0
	s_and_b64 s[0:1], vcc, exec
	s_cselect_b32 s0, 0xffffffc0, 0
	v_cndmask_b32_e32 v1, 0, v157, vcc
	v_sub_f32_e32 v0, v1, v0
	v_exp_f32_e32 v0, v0
	v_mov_b32_e32 v1, v152
	s_bitcmp0_b32 s9, 0
	v_ldexp_f32 v0, v0, s0
	v_mul_f32_e32 v138, 0x3fb8aa3b, v0
	v_bfe_u32 v0, v1, 3, 1
	v_lshlrev_b32_e32 v169, 3, v1
	v_mul_u32_u24_e32 v9, 0x2400, v0
	v_and_b32_e32 v0, 56, v169
	v_ashrrev_i32_e32 v2, 4, v1
	v_mad_u64_u32 v[4:5], s[34:35], v2, s80, v[0:1]
	v_ashrrev_i32_e32 v10, 3, v1
	v_lshl_add_u32 v175, v4, 1, v9
	v_mul_lo_u32 v4, v10, s80
	v_add_u32_e32 v11, 0x200, v1
	v_add_lshl_u32 v176, v4, v0, 1
	v_ashrrev_i32_e32 v4, 4, v11
	v_mad_u64_u32 v[6:7], s[34:35], v4, s80, v[0:1]
	v_lshl_add_u32 v177, v6, 1, v9
	v_ashrrev_i32_e32 v6, 3, v11
	v_mul_lo_u32 v7, v6, s80
	v_add_lshl_u32 v178, v7, v0, 1
	v_add_u32_e32 v0, 0, v175
	s_waitcnt vmcnt(3)
	ds_write_b128 v0, v[118:121]
	v_add_u32_e32 v0, 0, v176
	s_waitcnt vmcnt(2)
	ds_write_b128 v0, v[114:117] offset:18432
	v_add_u32_e32 v0, 0, v177
	s_waitcnt vmcnt(1)
	ds_write_b128 v0, v[122:125]
	v_add_u32_e32 v0, 0, v178
	v_lshlrev_b32_e32 v7, 1, v1
	v_lshrrev_b32_e32 v9, 1, v1
	s_waitcnt vmcnt(0)
	ds_write_b128 v0, v[126:129] offset:18432
	v_and_b32_e32 v0, 19, v1
	v_and_b32_e32 v7, 8, v7
	v_and_b32_e32 v9, 4, v9
	v_or3_b32 v0, v0, v7, v9
	v_mul_u32_u24_e32 v179, 0x90, v0
	v_and_b32_e32 v0, 7, v1
	v_lshlrev_b32_e32 v96, 4, v0
	v_add_u32_e32 v0, s8, v10
	v_and_b32_e32 v171, 31, v1
	v_readfirstlane_b32 s65, v1
	v_and_b32_e32 v168, 63, v1
	v_bfe_u32 v170, v1, 5, 1
	v_and_b32_e32 v8, 15, v1
	v_ashrrev_i32_e32 v1, 31, v0
	v_lshlrev_b64 v[0:1], 15, v[0:1]
	s_cselect_b64 s[0:1], -1, 0
	v_lshl_add_u64 v[144:145], s[42:43], 0, v[0:1]
	v_add_u32_e32 v0, s8, v6
	s_and_b64 s[34:35], s[0:1], exec
	v_ashrrev_i32_e32 v1, 31, v0
	s_cselect_b32 s38, s77, s78
	s_and_b32 s48, s65, 0x3fffffc0
	v_ashrrev_i32_e32 v3, 31, v2
	v_lshlrev_b64 v[0:1], 15, v[0:1]
	s_lshl_b32 s49, s38, 7
	s_lshl_b32 s34, s48, 2
	v_lshl_add_u64 v[146:147], s[42:43], 0, v[0:1]
	v_lshlrev_b64 v[0:1], 11, v[2:3]
	v_lshlrev_b32_e32 v2, 4, v8
	v_ashrrev_i32_e32 v5, 31, v4
	s_add_i32 s66, s34, 0
	s_or_b32 s34, s49, 0x7f
	v_or_b32_e32 v0, v0, v2
	s_bfe_u32 s64, s65, 0x20006
	v_cvt_f32_u32_e32 v181, s34
	v_lshl_add_u64 v[148:149], s[86:87], 0, v[0:1]
	v_lshlrev_b64 v[0:1], 11, v[4:5]
	s_lshl_b32 s39, s64, 5
	v_or_b32_e32 v0, v0, v2
	v_mov_b32_e32 v14, v97
	v_mov_b32_e32 v15, v97
	s_or_b32 s99, s39, s49
	s_lshl_b32 s69, s38, 1
	s_add_i32 s66, s66, 0x1b000
	v_lshl_add_u64 v[150:151], s[86:87], 0, v[0:1]
	v_mov_b32_e32 v0, v97
	v_mov_b32_e32 v1, v97
	v_mov_b32_e32 v2, v97
	v_mov_b32_e32 v3, v97
	v_mov_b32_e32 v4, v97
	v_mov_b32_e32 v5, v97
	v_mov_b32_e32 v6, v97
	v_mov_b32_e32 v7, v97
	v_mov_b32_e32 v8, v97
	v_mov_b32_e32 v9, v97
	v_mov_b32_e32 v10, v97
	v_mov_b32_e32 v11, v97
	v_mov_b32_e32 v12, v97
	v_mov_b32_e32 v13, v97
	v_mov_b64_e32 v[30:31], v[14:15]
	v_mov_b64_e32 v[46:47], v[14:15]
	v_mov_b64_e32 v[62:63], v[14:15]
	s_mov_b32 s68, 1
	s_ashr_i32 s67, s65, 8
	s_add_i32 s69, s69, 2
	v_lshlrev_b32_e32 v172, 4, v170
	v_mul_u32_u24_e32 v180, 0x90, v171
	s_or_b32 s70, s99, 31
	v_lshlrev_b32_e32 v182, 3, v170
	v_or_b32_e32 v183, s99, v171
	v_cmp_gt_u32_e64 s[38:39], 32, v168
	v_lshl_add_u32 v173, v171, 2, s66
	v_mov_b32_e32 v140, v138
	v_mov_b32_e32 v141, v138
	v_mov_b32_e32 v142, v138
	v_mov_b32_e32 v143, v138
	s_add_i32 s48, s49, 0x80
	v_mov_b32_e32 v174, 0
	s_mov_b32 s49, 0
	v_mov_b64_e32 v[28:29], v[12:13]
	v_mov_b64_e32 v[26:27], v[10:11]
	v_mov_b64_e32 v[24:25], v[8:9]
	v_mov_b64_e32 v[22:23], v[6:7]
	v_mov_b64_e32 v[20:21], v[4:5]
	v_mov_b64_e32 v[18:19], v[2:3]
	v_mov_b64_e32 v[16:17], v[0:1]
	v_mov_b64_e32 v[44:45], v[12:13]
	v_mov_b64_e32 v[42:43], v[10:11]
	v_mov_b64_e32 v[40:41], v[8:9]
	v_mov_b64_e32 v[38:39], v[6:7]
	v_mov_b64_e32 v[36:37], v[4:5]
	v_mov_b64_e32 v[34:35], v[2:3]
	v_mov_b64_e32 v[32:33], v[0:1]
	v_mov_b64_e32 v[60:61], v[12:13]
	v_mov_b64_e32 v[58:59], v[10:11]
	v_mov_b64_e32 v[56:57], v[8:9]
	v_mov_b64_e32 v[54:55], v[6:7]
	v_mov_b64_e32 v[52:53], v[4:5]
	v_mov_b64_e32 v[50:51], v[2:3]
	v_mov_b64_e32 v[48:49], v[0:1]
	s_mov_b32 s50, 0
	v_mov_b32_e32 v184, 0
	s_cmp_eq_u32 s9, 0
	s_cbranch_scc1 .Lattn_nodefer
	s_cmp_lg_u32 s67, 0
	s_cbranch_scc1 .Lattn_nodefer
	v_mov_b32_e32 v222, v220
	v_mov_b32_e32 v223, v97
	v_lshl_add_u64 v[222:223], v[218:219], 0, v[222:223]
	global_store_dwordx4 v[222:223], v[186:189], off nt
	v_or_b32_e32 v222, 0x2000, v220
	v_mov_b32_e32 v223, v97
	v_lshl_add_u64 v[222:223], v[218:219], 0, v[222:223]
	global_store_dwordx4 v[222:223], v[190:193], off nt
	v_or_b32_e32 v222, 0x4000, v220
	v_mov_b32_e32 v223, v97
	v_lshl_add_u64 v[222:223], v[218:219], 0, v[222:223]
	global_store_dwordx4 v[222:223], v[194:197], off nt
	v_or_b32_e32 v222, 0x6000, v220
	v_mov_b32_e32 v223, v97
	v_lshl_add_u64 v[222:223], v[218:219], 0, v[222:223]
	global_store_dwordx4 v[222:223], v[198:201], off nt
	v_or_b32_e32 v222, 0x8000, v220
	v_mov_b32_e32 v223, v97
	v_lshl_add_u64 v[222:223], v[218:219], 0, v[222:223]
	global_store_dwordx4 v[222:223], v[202:205], off nt
	v_or_b32_e32 v222, 0xa000, v220
	v_mov_b32_e32 v223, v97
	v_lshl_add_u64 v[222:223], v[218:219], 0, v[222:223]
	global_store_dwordx4 v[222:223], v[206:209], off nt
	v_or_b32_e32 v222, 0xc000, v220
	v_mov_b32_e32 v223, v97
	v_lshl_add_u64 v[222:223], v[218:219], 0, v[222:223]
	global_store_dwordx4 v[222:223], v[210:213], off nt
	v_or_b32_e32 v222, 0xe000, v220
	v_mov_b32_e32 v223, v97
	v_lshl_add_u64 v[222:223], v[218:219], 0, v[222:223]
	global_store_dwordx4 v[222:223], v[214:217], off nt
.Lattn_nodefer:
	s_waitcnt lgkmcnt(0)
	s_barrier
	s_branch .LBB0_278

.LBB0_303:
	s_cmpk_gt_u32 s65, 0xff
	s_waitcnt lgkmcnt(0)
	s_barrier
	s_cbranch_scc1 .LBB0_275
	s_mulk_i32 s64, 0x2200
	s_add_i32 s34, s64, 0
	s_add_i32 s34, s34, 0x10000
	ds_read2st64_b32 v[130:131], v71 offset1:1
	ds_read2st64_b32 v[132:133], v71 offset0:2 offset1:3
	ds_read2st64_b32 v[134:135], v71 offset0:4 offset1:5
	ds_read2st64_b32 v[136:137], v71 offset0:6 offset1:7
	ds_read2st64_b32 v[138:139], v71 offset0:8 offset1:9
	ds_read2st64_b32 v[140:141], v71 offset0:10 offset1:11
	ds_read2st64_b32 v[142:143], v71 offset0:12 offset1:13
	ds_read2st64_b32 v[144:145], v71 offset0:14 offset1:15
	ds_read2st64_b32 v[146:147], v71 offset0:16 offset1:17
	ds_read2st64_b32 v[148:149], v71 offset0:18 offset1:19
	ds_read2st64_b32 v[150:151], v71 offset0:20 offset1:21
	ds_read2st64_b32 v[172:173], v71 offset0:22 offset1:23
	ds_read2st64_b32 v[174:175], v71 offset0:24 offset1:25
	ds_read2st64_b32 v[176:177], v71 offset0:26 offset1:27
	ds_read2st64_b32 v[178:179], v71 offset0:28 offset1:29
	ds_read2st64_b32 v[180:181], v71 offset0:30 offset1:31
	ds_read2st64_b32 v[182:183], v71 offset0:32 offset1:33
	ds_read2st64_b32 v[184:185], v71 offset0:34 offset1:35
	ds_read2st64_b32 v[186:187], v71 offset0:36 offset1:37
	ds_read2st64_b32 v[188:189], v71 offset0:38 offset1:39
	ds_read2st64_b32 v[190:191], v71 offset0:40 offset1:41
	ds_read2st64_b32 v[192:193], v71 offset0:42 offset1:43
	ds_read2st64_b32 v[194:195], v71 offset0:44 offset1:45
	ds_read2st64_b32 v[196:197], v71 offset0:46 offset1:47
	ds_read2st64_b32 v[198:199], v71 offset0:48 offset1:49
	ds_read2st64_b32 v[200:201], v71 offset0:50 offset1:51
	ds_read2st64_b32 v[202:203], v71 offset0:52 offset1:53
	ds_read2st64_b32 v[204:205], v71 offset0:54 offset1:55
	ds_read2st64_b32 v[206:207], v71 offset0:56 offset1:57
	ds_read2st64_b32 v[208:209], v71 offset0:58 offset1:59
	ds_read2st64_b32 v[210:211], v71 offset0:60 offset1:61
	ds_read2st64_b32 v[212:213], v71 offset0:62 offset1:63
	s_waitcnt lgkmcnt(15)
	v_sub_f32_e32 v60, v72, v130
	v_sub_f32_e32 v55, v0, v131
	v_sub_f32_e32 v52, v73, v132
	v_sub_f32_e32 v47, v74, v133
	v_sub_f32_e32 v44, v3, v134
	v_sub_f32_e32 v39, v36, v135
	v_sub_f32_e32 v28, v23, v138
	v_sub_f32_e32 v23, v38, v139
	v_sub_f32_e32 v36, v20, v136
	v_sub_f32_e32 v31, v6, v137
	v_sub_f32_e32 v20, v41, v140
	v_sub_f32_e32 v15, v26, v141
	v_sub_f32_e32 v12, v54, v142
	v_sub_f32_e32 v6, v77, v143
	v_sub_f32_e32 v3, v57, v144
	v_sub_f32_e32 v0, v14, v145
	v_sub_f32_e32 v62, v68, v146
	v_sub_f32_e32 v57, v49, v147
	v_sub_f32_e32 v54, v1, v148
	v_sub_f32_e32 v49, v18, v149
	v_sub_f32_e32 v46, v34, v150
	v_sub_f32_e32 v41, v51, v151
	v_sub_f32_e32 v38, v5, v172
	v_sub_f32_e32 v34, v22, v173
	v_sub_f32_e32 v30, v40, v174
	v_sub_f32_e32 v26, v56, v175
	v_sub_f32_e32 v22, v75, v176
	v_sub_f32_e32 v18, v10, v177
	v_sub_f32_e32 v14, v27, v178
	v_sub_f32_e32 v10, v59, v179
	v_sub_f32_e32 v5, v43, v180
	v_sub_f32_e32 v1, v76, v181
	v_sub_f32_e32 v74, v16, v182
	v_sub_f32_e32 v59, v32, v183
	s_waitcnt lgkmcnt(14)
	v_sub_f32_e32 v56, v48, v184
	v_sub_f32_e32 v51, v2, v185
	s_waitcnt lgkmcnt(13)
	v_sub_f32_e32 v48, v19, v186
	v_sub_f32_e32 v43, v53, v187
	s_waitcnt lgkmcnt(12)
	v_sub_f32_e32 v40, v35, v188
	v_sub_f32_e32 v35, v69, v189
	s_waitcnt lgkmcnt(11)
	v_sub_f32_e32 v32, v7, v190
	v_sub_f32_e32 v27, v24, v191
	s_waitcnt lgkmcnt(10)
	v_sub_f32_e32 v24, v42, v192
	v_sub_f32_e32 v19, v58, v193
	s_waitcnt lgkmcnt(9)
	v_sub_f32_e32 v16, v11, v194
	v_sub_f32_e32 v11, v29, v195
	s_waitcnt lgkmcnt(8)
	v_sub_f32_e32 v7, v45, v196
	v_sub_f32_e32 v2, v61, v197
	s_waitcnt lgkmcnt(7)
	v_sub_f32_e32 v72, v64, v198
	v_sub_f32_e32 v61, v17, v199
	s_waitcnt lgkmcnt(6)
	v_sub_f32_e32 v58, v33, v200
	v_sub_f32_e32 v53, v50, v201
	s_waitcnt lgkmcnt(5)
	v_sub_f32_e32 v50, v4, v202
	v_sub_f32_e32 v45, v21, v203
	s_waitcnt lgkmcnt(4)
	v_sub_f32_e32 v42, v37, v204
	v_sub_f32_e32 v37, v65, v205
	s_waitcnt lgkmcnt(3)
	v_sub_f32_e32 v33, v8, v206
	v_sub_f32_e32 v29, v9, v207
	s_waitcnt lgkmcnt(2)
	v_sub_f32_e32 v25, v25, v208
	v_sub_f32_e32 v21, v66, v209
	s_waitcnt lgkmcnt(0)
	v_sub_f32_e32 v4, v63, v213
	v_sub_f32_e32 v13, v13, v211
	v_sub_f32_e32 v9, v70, v212
	v_sub_f32_e32 v17, v67, v210
	s_waitcnt lgkmcnt(0)
	v_mul_f32_e32 v130, v62, v62
	v_fmac_f32_e32 v130, v60, v60
	v_fmac_f32_e32 v130, v74, v74
	v_fmac_f32_e32 v130, v72, v72
	v_mul_f32_e32 v131, v57, v57
	v_fmac_f32_e32 v131, v55, v55
	v_fmac_f32_e32 v131, v59, v59
	v_fmac_f32_e32 v131, v61, v61
	v_mul_f32_e32 v132, v54, v54
	v_fmac_f32_e32 v132, v52, v52
	v_fmac_f32_e32 v132, v56, v56
	v_fmac_f32_e32 v132, v58, v58
	v_mul_f32_e32 v133, v49, v49
	v_fmac_f32_e32 v133, v47, v47
	v_fmac_f32_e32 v133, v51, v51
	v_fmac_f32_e32 v133, v53, v53
	v_mul_f32_e32 v134, v46, v46
	v_fmac_f32_e32 v134, v44, v44
	v_fmac_f32_e32 v134, v48, v48
	v_fmac_f32_e32 v134, v50, v50
	v_mul_f32_e32 v135, v41, v41
	v_fmac_f32_e32 v135, v39, v39
	v_fmac_f32_e32 v135, v43, v43
	v_fmac_f32_e32 v135, v45, v45
	v_mul_f32_e32 v136, v38, v38
	v_fmac_f32_e32 v136, v36, v36
	v_fmac_f32_e32 v136, v40, v40
	v_fmac_f32_e32 v136, v42, v42
	v_mul_f32_e32 v137, v34, v34
	v_fmac_f32_e32 v137, v31, v31
	v_fmac_f32_e32 v137, v35, v35
	v_fmac_f32_e32 v137, v37, v37
	v_mul_f32_e32 v138, v30, v30
	v_fmac_f32_e32 v138, v28, v28
	v_fmac_f32_e32 v138, v32, v32
	v_fmac_f32_e32 v138, v33, v33
	v_mul_f32_e32 v139, v26, v26
	v_fmac_f32_e32 v139, v23, v23
	v_fmac_f32_e32 v139, v27, v27
	v_fmac_f32_e32 v139, v29, v29
	v_mul_f32_e32 v140, v22, v22
	v_fmac_f32_e32 v140, v20, v20
	v_fmac_f32_e32 v140, v24, v24
	v_fmac_f32_e32 v140, v25, v25
	v_mul_f32_e32 v141, v18, v18
	v_fmac_f32_e32 v141, v15, v15
	v_fmac_f32_e32 v141, v19, v19
	v_fmac_f32_e32 v141, v21, v21
	v_mul_f32_e32 v142, v14, v14
	v_fmac_f32_e32 v142, v12, v12
	v_fmac_f32_e32 v142, v16, v16
	v_fmac_f32_e32 v142, v17, v17
	v_mul_f32_e32 v143, v10, v10
	v_fmac_f32_e32 v143, v6, v6
	v_fmac_f32_e32 v143, v11, v11
	v_fmac_f32_e32 v143, v13, v13
	v_mul_f32_e32 v144, v5, v5
	v_fmac_f32_e32 v144, v3, v3
	v_fmac_f32_e32 v144, v7, v7
	v_fmac_f32_e32 v144, v9, v9
	v_mul_f32_e32 v145, v1, v1
	v_fmac_f32_e32 v145, v0, v0
	v_fmac_f32_e32 v145, v2, v2
	v_fmac_f32_e32 v145, v4, v4
	ds_bpermute_b32 v146, v161, v130
	ds_bpermute_b32 v147, v161, v131
	ds_bpermute_b32 v148, v161, v132
	ds_bpermute_b32 v149, v161, v133
	ds_bpermute_b32 v150, v161, v134
	ds_bpermute_b32 v151, v161, v135
	ds_bpermute_b32 v172, v161, v136
	ds_bpermute_b32 v173, v161, v137
	ds_bpermute_b32 v174, v161, v138
	ds_bpermute_b32 v175, v161, v139
	ds_bpermute_b32 v176, v161, v140
	ds_bpermute_b32 v177, v161, v141
	ds_bpermute_b32 v178, v161, v142
	ds_bpermute_b32 v179, v161, v143
	ds_bpermute_b32 v180, v161, v144
	ds_bpermute_b32 v181, v161, v145
	s_waitcnt lgkmcnt(15)
	v_add_f32_e32 v130, v130, v146
	s_waitcnt lgkmcnt(14)
	v_add_f32_e32 v131, v131, v147
	s_waitcnt lgkmcnt(13)
	v_add_f32_e32 v132, v132, v148
	s_waitcnt lgkmcnt(12)
	v_add_f32_e32 v133, v133, v149
	s_waitcnt lgkmcnt(11)
	v_add_f32_e32 v134, v134, v150
	s_waitcnt lgkmcnt(10)
	v_add_f32_e32 v135, v135, v151
	s_waitcnt lgkmcnt(9)
	v_add_f32_e32 v136, v136, v172
	s_waitcnt lgkmcnt(8)
	v_add_f32_e32 v137, v137, v173
	s_waitcnt lgkmcnt(7)
	v_add_f32_e32 v138, v138, v174
	s_waitcnt lgkmcnt(6)
	v_add_f32_e32 v139, v139, v175
	s_waitcnt lgkmcnt(5)
	v_add_f32_e32 v140, v140, v176
	s_waitcnt lgkmcnt(4)
	v_add_f32_e32 v141, v141, v177
	s_waitcnt lgkmcnt(3)
	v_add_f32_e32 v142, v142, v178
	s_waitcnt lgkmcnt(2)
	v_add_f32_e32 v143, v143, v179
	s_waitcnt lgkmcnt(1)
	v_add_f32_e32 v144, v144, v180
	s_waitcnt lgkmcnt(0)
	v_add_f32_e32 v145, v145, v181
	ds_bpermute_b32 v146, v162, v130
	ds_bpermute_b32 v147, v162, v131
	ds_bpermute_b32 v148, v162, v132
	ds_bpermute_b32 v149, v162, v133
	ds_bpermute_b32 v150, v162, v134
	ds_bpermute_b32 v151, v162, v135
	ds_bpermute_b32 v172, v162, v136
	ds_bpermute_b32 v173, v162, v137
	ds_bpermute_b32 v174, v162, v138
	ds_bpermute_b32 v175, v162, v139
	ds_bpermute_b32 v176, v162, v140
	ds_bpermute_b32 v177, v162, v141
	ds_bpermute_b32 v178, v162, v142
	ds_bpermute_b32 v179, v162, v143
	ds_bpermute_b32 v180, v162, v144
	ds_bpermute_b32 v181, v162, v145
	s_waitcnt lgkmcnt(15)
	v_add_f32_e32 v130, v130, v146
	s_waitcnt lgkmcnt(14)
	v_add_f32_e32 v131, v131, v147
	s_waitcnt lgkmcnt(13)
	v_add_f32_e32 v132, v132, v148
	s_waitcnt lgkmcnt(12)
	v_add_f32_e32 v133, v133, v149
	s_waitcnt lgkmcnt(11)
	v_add_f32_e32 v134, v134, v150
	s_waitcnt lgkmcnt(10)
	v_add_f32_e32 v135, v135, v151
	s_waitcnt lgkmcnt(9)
	v_add_f32_e32 v136, v136, v172
	s_waitcnt lgkmcnt(8)
	v_add_f32_e32 v137, v137, v173
	s_waitcnt lgkmcnt(7)
	v_add_f32_e32 v138, v138, v174
	s_waitcnt lgkmcnt(6)
	v_add_f32_e32 v139, v139, v175
	s_waitcnt lgkmcnt(5)
	v_add_f32_e32 v140, v140, v176
	s_waitcnt lgkmcnt(4)
	v_add_f32_e32 v141, v141, v177
	s_waitcnt lgkmcnt(3)
	v_add_f32_e32 v142, v142, v178
	s_waitcnt lgkmcnt(2)
	v_add_f32_e32 v143, v143, v179
	s_waitcnt lgkmcnt(1)
	v_add_f32_e32 v144, v144, v180
	s_waitcnt lgkmcnt(0)
	v_add_f32_e32 v145, v145, v181
	ds_bpermute_b32 v146, v163, v130
	ds_bpermute_b32 v147, v163, v131
	ds_bpermute_b32 v148, v163, v132
	ds_bpermute_b32 v149, v163, v133
	ds_bpermute_b32 v150, v163, v134
	ds_bpermute_b32 v151, v163, v135
	ds_bpermute_b32 v172, v163, v136
	ds_bpermute_b32 v173, v163, v137
	ds_bpermute_b32 v174, v163, v138
	ds_bpermute_b32 v175, v163, v139
	ds_bpermute_b32 v176, v163, v140
	ds_bpermute_b32 v177, v163, v141
	ds_bpermute_b32 v178, v163, v142
	ds_bpermute_b32 v179, v163, v143
	ds_bpermute_b32 v180, v163, v144
	ds_bpermute_b32 v181, v163, v145
	s_waitcnt lgkmcnt(15)
	v_add_f32_e32 v130, v130, v146
	s_waitcnt lgkmcnt(14)
	v_add_f32_e32 v131, v131, v147
	s_waitcnt lgkmcnt(13)
	v_add_f32_e32 v132, v132, v148
	s_waitcnt lgkmcnt(12)
	v_add_f32_e32 v133, v133, v149
	s_waitcnt lgkmcnt(11)
	v_add_f32_e32 v134, v134, v150
	s_waitcnt lgkmcnt(10)
	v_add_f32_e32 v135, v135, v151
	s_waitcnt lgkmcnt(9)
	v_add_f32_e32 v136, v136, v172
	s_waitcnt lgkmcnt(8)
	v_add_f32_e32 v137, v137, v173
	s_waitcnt lgkmcnt(7)
	v_add_f32_e32 v138, v138, v174
	s_waitcnt lgkmcnt(6)
	v_add_f32_e32 v139, v139, v175
	s_waitcnt lgkmcnt(5)
	v_add_f32_e32 v140, v140, v176
	s_waitcnt lgkmcnt(4)
	v_add_f32_e32 v141, v141, v177
	s_waitcnt lgkmcnt(3)
	v_add_f32_e32 v142, v142, v178
	s_waitcnt lgkmcnt(2)
	v_add_f32_e32 v143, v143, v179
	s_waitcnt lgkmcnt(1)
	v_add_f32_e32 v144, v144, v180
	s_waitcnt lgkmcnt(0)
	v_add_f32_e32 v145, v145, v181
	ds_bpermute_b32 v146, v164, v130
	ds_bpermute_b32 v147, v164, v131
	ds_bpermute_b32 v148, v164, v132
	ds_bpermute_b32 v149, v164, v133
	ds_bpermute_b32 v150, v164, v134
	ds_bpermute_b32 v151, v164, v135
	ds_bpermute_b32 v172, v164, v136
	ds_bpermute_b32 v173, v164, v137
	ds_bpermute_b32 v174, v164, v138
	ds_bpermute_b32 v175, v164, v139
	ds_bpermute_b32 v176, v164, v140
	ds_bpermute_b32 v177, v164, v141
	ds_bpermute_b32 v178, v164, v142
	ds_bpermute_b32 v179, v164, v143
	ds_bpermute_b32 v180, v164, v144
	ds_bpermute_b32 v181, v164, v145
	s_waitcnt lgkmcnt(15)
	v_add_f32_e32 v130, v130, v146
	s_waitcnt lgkmcnt(14)
	v_add_f32_e32 v131, v131, v147
	s_waitcnt lgkmcnt(13)
	v_add_f32_e32 v132, v132, v148
	s_waitcnt lgkmcnt(12)
	v_add_f32_e32 v133, v133, v149
	s_waitcnt lgkmcnt(11)
	v_add_f32_e32 v134, v134, v150
	s_waitcnt lgkmcnt(10)
	v_add_f32_e32 v135, v135, v151
	s_waitcnt lgkmcnt(9)
	v_add_f32_e32 v136, v136, v172
	s_waitcnt lgkmcnt(8)
	v_add_f32_e32 v137, v137, v173
	s_waitcnt lgkmcnt(7)
	v_add_f32_e32 v138, v138, v174
	s_waitcnt lgkmcnt(6)
	v_add_f32_e32 v139, v139, v175
	s_waitcnt lgkmcnt(5)
	v_add_f32_e32 v140, v140, v176
	s_waitcnt lgkmcnt(4)
	v_add_f32_e32 v141, v141, v177
	s_waitcnt lgkmcnt(3)
	v_add_f32_e32 v142, v142, v178
	s_waitcnt lgkmcnt(2)
	v_add_f32_e32 v143, v143, v179
	s_waitcnt lgkmcnt(1)
	v_add_f32_e32 v144, v144, v180
	s_waitcnt lgkmcnt(0)
	v_add_f32_e32 v145, v145, v181
	ds_bpermute_b32 v146, v165, v130
	ds_bpermute_b32 v147, v165, v131
	ds_bpermute_b32 v148, v165, v132
	ds_bpermute_b32 v149, v165, v133
	ds_bpermute_b32 v150, v165, v134
	ds_bpermute_b32 v151, v165, v135
	ds_bpermute_b32 v172, v165, v136
	ds_bpermute_b32 v173, v165, v137
	ds_bpermute_b32 v174, v165, v138
	ds_bpermute_b32 v175, v165, v139
	ds_bpermute_b32 v176, v165, v140
	ds_bpermute_b32 v177, v165, v141
	ds_bpermute_b32 v178, v165, v142
	ds_bpermute_b32 v179, v165, v143
	ds_bpermute_b32 v180, v165, v144
	ds_bpermute_b32 v181, v165, v145
	s_waitcnt lgkmcnt(15)
	v_add_f32_e32 v130, v130, v146
	s_waitcnt lgkmcnt(14)
	v_add_f32_e32 v131, v131, v147
	s_waitcnt lgkmcnt(13)
	v_add_f32_e32 v132, v132, v148
	s_waitcnt lgkmcnt(12)
	v_add_f32_e32 v133, v133, v149
	s_waitcnt lgkmcnt(11)
	v_add_f32_e32 v134, v134, v150
	s_waitcnt lgkmcnt(10)
	v_add_f32_e32 v135, v135, v151
	s_waitcnt lgkmcnt(9)
	v_add_f32_e32 v136, v136, v172
	s_waitcnt lgkmcnt(8)
	v_add_f32_e32 v137, v137, v173
	s_waitcnt lgkmcnt(7)
	v_add_f32_e32 v138, v138, v174
	s_waitcnt lgkmcnt(6)
	v_add_f32_e32 v139, v139, v175
	s_waitcnt lgkmcnt(5)
	v_add_f32_e32 v140, v140, v176
	s_waitcnt lgkmcnt(4)
	v_add_f32_e32 v141, v141, v177
	s_waitcnt lgkmcnt(3)
	v_add_f32_e32 v142, v142, v178
	s_waitcnt lgkmcnt(2)
	v_add_f32_e32 v143, v143, v179
	s_waitcnt lgkmcnt(1)
	v_add_f32_e32 v144, v144, v180
	s_waitcnt lgkmcnt(0)
	v_add_f32_e32 v145, v145, v181
	v_fmamk_f32 v130, v130, 0x3c000000, v153
	v_fmamk_f32 v131, v131, 0x3c000000, v153
	v_fmamk_f32 v132, v132, 0x3c000000, v153
	v_fmamk_f32 v133, v133, 0x3c000000, v153
	v_fmamk_f32 v134, v134, 0x3c000000, v153
	v_fmamk_f32 v135, v135, 0x3c000000, v153
	v_fmamk_f32 v136, v136, 0x3c000000, v153
	v_fmamk_f32 v137, v137, 0x3c000000, v153
	v_fmamk_f32 v138, v138, 0x3c000000, v153
	v_fmamk_f32 v139, v139, 0x3c000000, v153
	v_fmamk_f32 v140, v140, 0x3c000000, v153
	v_fmamk_f32 v141, v141, 0x3c000000, v153
	v_fmamk_f32 v142, v142, 0x3c000000, v153
	v_fmamk_f32 v143, v143, 0x3c000000, v153
	v_fmamk_f32 v144, v144, 0x3c000000, v153
	v_fmamk_f32 v145, v145, 0x3c000000, v153
	v_rsq_f32_e32 v130, v130
	v_rsq_f32_e32 v131, v131
	v_rsq_f32_e32 v132, v132
	v_rsq_f32_e32 v133, v133
	v_rsq_f32_e32 v134, v134
	v_rsq_f32_e32 v135, v135
	v_rsq_f32_e32 v136, v136
	v_rsq_f32_e32 v137, v137
	v_rsq_f32_e32 v138, v138
	v_rsq_f32_e32 v139, v139
	v_rsq_f32_e32 v140, v140
	v_rsq_f32_e32 v141, v141
	v_rsq_f32_e32 v142, v142
	v_rsq_f32_e32 v143, v143
	v_rsq_f32_e32 v144, v144
	v_rsq_f32_e32 v145, v145
	v_lshlrev_b32_e32 v190, 1, v171
	v_mul_u32_u24_e32 v191, 0x440, v170
	v_add3_u32 v190, s34, v190, v191
	v_mul_f32_e32 v182, v60, v130
	v_bfe_u32 v186, v182, 16, 1
	v_add3_u32 v182, v182, v186, s81
	ds_write_b16_d16_hi v190, v182
	v_mul_f32_e32 v183, v62, v130
	v_bfe_u32 v187, v183, 16, 1
	v_add3_u32 v183, v183, v187, s81
	ds_write_b16_d16_hi v190, v183 offset:64
	v_mul_f32_e32 v184, v74, v130
	v_bfe_u32 v188, v184, 16, 1
	v_add3_u32 v184, v184, v188, s81
	ds_write_b16_d16_hi v190, v184 offset:128
	v_mul_f32_e32 v185, v72, v130
	v_bfe_u32 v189, v185, 16, 1
	v_add3_u32 v185, v185, v189, s81
	ds_write_b16_d16_hi v190, v185 offset:192
	v_mul_f32_e32 v182, v55, v131
	v_bfe_u32 v186, v182, 16, 1
	v_add3_u32 v182, v182, v186, s81
	ds_write_b16_d16_hi v190, v182 offset:272
	v_mul_f32_e32 v183, v57, v131
	v_bfe_u32 v187, v183, 16, 1
	v_add3_u32 v183, v183, v187, s81
	ds_write_b16_d16_hi v190, v183 offset:336
	v_mul_f32_e32 v184, v59, v131
	v_bfe_u32 v188, v184, 16, 1
	v_add3_u32 v184, v184, v188, s81
	ds_write_b16_d16_hi v190, v184 offset:400
	v_mul_f32_e32 v185, v61, v131
	v_bfe_u32 v189, v185, 16, 1
	v_add3_u32 v185, v185, v189, s81
	ds_write_b16_d16_hi v190, v185 offset:464
	v_mul_f32_e32 v182, v52, v132
	v_bfe_u32 v186, v182, 16, 1
	v_add3_u32 v182, v182, v186, s81
	ds_write_b16_d16_hi v190, v182 offset:544
	v_mul_f32_e32 v183, v54, v132
	v_bfe_u32 v187, v183, 16, 1
	v_add3_u32 v183, v183, v187, s81
	ds_write_b16_d16_hi v190, v183 offset:608
	v_mul_f32_e32 v184, v56, v132
	v_bfe_u32 v188, v184, 16, 1
	v_add3_u32 v184, v184, v188, s81
	ds_write_b16_d16_hi v190, v184 offset:672
	v_mul_f32_e32 v185, v58, v132
	v_bfe_u32 v189, v185, 16, 1
	v_add3_u32 v185, v185, v189, s81
	ds_write_b16_d16_hi v190, v185 offset:736
	v_mul_f32_e32 v182, v47, v133
	v_bfe_u32 v186, v182, 16, 1
	v_add3_u32 v182, v182, v186, s81
	ds_write_b16_d16_hi v190, v182 offset:816
	v_mul_f32_e32 v183, v49, v133
	v_bfe_u32 v187, v183, 16, 1
	v_add3_u32 v183, v183, v187, s81
	ds_write_b16_d16_hi v190, v183 offset:880
	v_mul_f32_e32 v184, v51, v133
	v_bfe_u32 v188, v184, 16, 1
	v_add3_u32 v184, v184, v188, s81
	ds_write_b16_d16_hi v190, v184 offset:944
	v_mul_f32_e32 v185, v53, v133
	v_bfe_u32 v189, v185, 16, 1
	v_add3_u32 v185, v185, v189, s81
	ds_write_b16_d16_hi v190, v185 offset:1008
	v_mul_f32_e32 v182, v44, v134
	v_bfe_u32 v186, v182, 16, 1
	v_add3_u32 v182, v182, v186, s81
	ds_write_b16_d16_hi v190, v182 offset:2176
	v_mul_f32_e32 v183, v46, v134
	v_bfe_u32 v187, v183, 16, 1
	v_add3_u32 v183, v183, v187, s81
	ds_write_b16_d16_hi v190, v183 offset:2240
	v_mul_f32_e32 v184, v48, v134
	v_bfe_u32 v188, v184, 16, 1
	v_add3_u32 v184, v184, v188, s81
	ds_write_b16_d16_hi v190, v184 offset:2304
	v_mul_f32_e32 v185, v50, v134
	v_bfe_u32 v189, v185, 16, 1
	v_add3_u32 v185, v185, v189, s81
	ds_write_b16_d16_hi v190, v185 offset:2368
	v_mul_f32_e32 v182, v39, v135
	v_bfe_u32 v186, v182, 16, 1
	v_add3_u32 v182, v182, v186, s81
	ds_write_b16_d16_hi v190, v182 offset:2448
	v_mul_f32_e32 v183, v41, v135
	v_bfe_u32 v187, v183, 16, 1
	v_add3_u32 v183, v183, v187, s81
	ds_write_b16_d16_hi v190, v183 offset:2512
	v_mul_f32_e32 v184, v43, v135
	v_bfe_u32 v188, v184, 16, 1
	v_add3_u32 v184, v184, v188, s81
	ds_write_b16_d16_hi v190, v184 offset:2576
	v_mul_f32_e32 v185, v45, v135
	v_bfe_u32 v189, v185, 16, 1
	v_add3_u32 v185, v185, v189, s81
	ds_write_b16_d16_hi v190, v185 offset:2640
	v_mul_f32_e32 v182, v36, v136
	v_bfe_u32 v186, v182, 16, 1
	v_add3_u32 v182, v182, v186, s81
	ds_write_b16_d16_hi v190, v182 offset:2720
	v_mul_f32_e32 v183, v38, v136
	v_bfe_u32 v187, v183, 16, 1
	v_add3_u32 v183, v183, v187, s81
	ds_write_b16_d16_hi v190, v183 offset:2784
	v_mul_f32_e32 v184, v40, v136
	v_bfe_u32 v188, v184, 16, 1
	v_add3_u32 v184, v184, v188, s81
	ds_write_b16_d16_hi v190, v184 offset:2848
	v_mul_f32_e32 v185, v42, v136
	v_bfe_u32 v189, v185, 16, 1
	v_add3_u32 v185, v185, v189, s81
	ds_write_b16_d16_hi v190, v185 offset:2912
	v_mul_f32_e32 v182, v31, v137
	v_bfe_u32 v186, v182, 16, 1
	v_add3_u32 v182, v182, v186, s81
	ds_write_b16_d16_hi v190, v182 offset:2992
	v_mul_f32_e32 v183, v34, v137
	v_bfe_u32 v187, v183, 16, 1
	v_add3_u32 v183, v183, v187, s81
	ds_write_b16_d16_hi v190, v183 offset:3056
	v_mul_f32_e32 v184, v35, v137
	v_bfe_u32 v188, v184, 16, 1
	v_add3_u32 v184, v184, v188, s81
	ds_write_b16_d16_hi v190, v184 offset:3120
	v_mul_f32_e32 v185, v37, v137
	v_bfe_u32 v189, v185, 16, 1
	v_add3_u32 v185, v185, v189, s81
	ds_write_b16_d16_hi v190, v185 offset:3184
	v_mul_f32_e32 v182, v28, v138
	v_bfe_u32 v186, v182, 16, 1
	v_add3_u32 v182, v182, v186, s81
	ds_write_b16_d16_hi v190, v182 offset:4352
	v_mul_f32_e32 v183, v30, v138
	v_bfe_u32 v187, v183, 16, 1
	v_add3_u32 v183, v183, v187, s81
	ds_write_b16_d16_hi v190, v183 offset:4416
	v_mul_f32_e32 v184, v32, v138
	v_bfe_u32 v188, v184, 16, 1
	v_add3_u32 v184, v184, v188, s81
	ds_write_b16_d16_hi v190, v184 offset:4480
	v_mul_f32_e32 v185, v33, v138
	v_bfe_u32 v189, v185, 16, 1
	v_add3_u32 v185, v185, v189, s81
	ds_write_b16_d16_hi v190, v185 offset:4544
	v_mul_f32_e32 v182, v23, v139
	v_bfe_u32 v186, v182, 16, 1
	v_add3_u32 v182, v182, v186, s81
	ds_write_b16_d16_hi v190, v182 offset:4624
	v_mul_f32_e32 v183, v26, v139
	v_bfe_u32 v187, v183, 16, 1
	v_add3_u32 v183, v183, v187, s81
	ds_write_b16_d16_hi v190, v183 offset:4688
	v_mul_f32_e32 v184, v27, v139
	v_bfe_u32 v188, v184, 16, 1
	v_add3_u32 v184, v184, v188, s81
	ds_write_b16_d16_hi v190, v184 offset:4752
	v_mul_f32_e32 v185, v29, v139
	v_bfe_u32 v189, v185, 16, 1
	v_add3_u32 v185, v185, v189, s81
	ds_write_b16_d16_hi v190, v185 offset:4816
	v_mul_f32_e32 v182, v20, v140
	v_bfe_u32 v186, v182, 16, 1
	v_add3_u32 v182, v182, v186, s81
	ds_write_b16_d16_hi v190, v182 offset:4896
	v_mul_f32_e32 v183, v22, v140
	v_bfe_u32 v187, v183, 16, 1
	v_add3_u32 v183, v183, v187, s81
	ds_write_b16_d16_hi v190, v183 offset:4960
	v_mul_f32_e32 v184, v24, v140
	v_bfe_u32 v188, v184, 16, 1
	v_add3_u32 v184, v184, v188, s81
	ds_write_b16_d16_hi v190, v184 offset:5024
	v_mul_f32_e32 v185, v25, v140
	v_bfe_u32 v189, v185, 16, 1
	v_add3_u32 v185, v185, v189, s81
	ds_write_b16_d16_hi v190, v185 offset:5088
	v_mul_f32_e32 v182, v15, v141
	v_bfe_u32 v186, v182, 16, 1
	v_add3_u32 v182, v182, v186, s81
	ds_write_b16_d16_hi v190, v182 offset:5168
	v_mul_f32_e32 v183, v18, v141
	v_bfe_u32 v187, v183, 16, 1
	v_add3_u32 v183, v183, v187, s81
	ds_write_b16_d16_hi v190, v183 offset:5232
	v_mul_f32_e32 v184, v19, v141
	v_bfe_u32 v188, v184, 16, 1
	v_add3_u32 v184, v184, v188, s81
	ds_write_b16_d16_hi v190, v184 offset:5296
	v_mul_f32_e32 v185, v21, v141
	v_bfe_u32 v189, v185, 16, 1
	v_add3_u32 v185, v185, v189, s81
	ds_write_b16_d16_hi v190, v185 offset:5360
	v_mul_f32_e32 v182, v12, v142
	v_bfe_u32 v186, v182, 16, 1
	v_add3_u32 v182, v182, v186, s81
	ds_write_b16_d16_hi v190, v182 offset:6528
	v_mul_f32_e32 v183, v14, v142
	v_bfe_u32 v187, v183, 16, 1
	v_add3_u32 v183, v183, v187, s81
	ds_write_b16_d16_hi v190, v183 offset:6592
	v_mul_f32_e32 v184, v16, v142
	v_bfe_u32 v188, v184, 16, 1
	v_add3_u32 v184, v184, v188, s81
	ds_write_b16_d16_hi v190, v184 offset:6656
	v_mul_f32_e32 v185, v17, v142
	v_bfe_u32 v189, v185, 16, 1
	v_add3_u32 v185, v185, v189, s81
	ds_write_b16_d16_hi v190, v185 offset:6720
	v_mul_f32_e32 v182, v6, v143
	v_bfe_u32 v186, v182, 16, 1
	v_add3_u32 v182, v182, v186, s81
	ds_write_b16_d16_hi v190, v182 offset:6800
	v_mul_f32_e32 v183, v10, v143
	v_bfe_u32 v187, v183, 16, 1
	v_add3_u32 v183, v183, v187, s81
	ds_write_b16_d16_hi v190, v183 offset:6864
	v_mul_f32_e32 v184, v11, v143
	v_bfe_u32 v188, v184, 16, 1
	v_add3_u32 v184, v184, v188, s81
	ds_write_b16_d16_hi v190, v184 offset:6928
	v_mul_f32_e32 v185, v13, v143
	v_bfe_u32 v189, v185, 16, 1
	v_add3_u32 v185, v185, v189, s81
	ds_write_b16_d16_hi v190, v185 offset:6992
	v_mul_f32_e32 v182, v3, v144
	v_bfe_u32 v186, v182, 16, 1
	v_add3_u32 v182, v182, v186, s81
	ds_write_b16_d16_hi v190, v182 offset:7072
	v_mul_f32_e32 v183, v5, v144
	v_bfe_u32 v187, v183, 16, 1
	v_add3_u32 v183, v183, v187, s81
	ds_write_b16_d16_hi v190, v183 offset:7136
	v_mul_f32_e32 v184, v7, v144
	v_bfe_u32 v188, v184, 16, 1
	v_add3_u32 v184, v184, v188, s81
	ds_write_b16_d16_hi v190, v184 offset:7200
	v_mul_f32_e32 v185, v9, v144
	v_bfe_u32 v189, v185, 16, 1
	v_add3_u32 v185, v185, v189, s81
	ds_write_b16_d16_hi v190, v185 offset:7264
	v_mul_f32_e32 v182, v0, v145
	v_bfe_u32 v186, v182, 16, 1
	v_add3_u32 v182, v182, v186, s81
	ds_write_b16_d16_hi v190, v182 offset:7344
	v_mul_f32_e32 v183, v1, v145
	v_bfe_u32 v187, v183, 16, 1
	v_add3_u32 v183, v183, v187, s81
	ds_write_b16_d16_hi v190, v183 offset:7408
	v_mul_f32_e32 v184, v2, v145
	v_bfe_u32 v188, v184, 16, 1
	v_add3_u32 v184, v184, v188, s81
	ds_write_b16_d16_hi v190, v184 offset:7472
	v_mul_f32_e32 v185, v4, v145
	v_bfe_u32 v189, v185, 16, 1
	v_add3_u32 v185, v185, v189, s81
	ds_write_b16_d16_hi v190, v185 offset:7536
	s_or_b32 s0, s40, s99
	s_mov_b32 s1, s41
	s_lshl_b64 s[0:1], s[0:1], 11
	v_lshlrev_b32_e32 v0, 1, v169
	v_lshrrev_b32_e32 v6, 4, v168
	v_and_b32_e32 v96, 0xf0, v0
	v_mul_u32_u24_e32 v0, 0x110, v6
	s_add_u32 s0, s92, s0
	v_add3_u32 v8, s34, v96, v0
	s_addc_u32 s1, s93, s1
	s_lshl_b32 s35, s98, 8
	s_add_u32 s0, s0, s35
	s_addc_u32 s1, s1, 0
	s_waitcnt lgkmcnt(0)
	ds_read_b128 v[186:189], v8
	ds_read_b128 v[190:193], v8 offset:1088
	ds_read_b128 v[194:197], v8 offset:2176
	ds_read_b128 v[198:201], v8 offset:3264
	ds_read_b128 v[202:205], v8 offset:4352
	ds_read_b128 v[206:209], v8 offset:5440
	ds_read_b128 v[210:213], v8 offset:6528
	ds_read_b128 v[214:217], v8 offset:7616
	v_lshl_add_u64 v[218:219], s[0:1], 0, v[96:97]
	v_lshlrev_b32_e32 v220, 11, v6
	s_cmp_lt_u32 s9, 3
	s_cbranch_scc1 .Lattn_epi_defer
	v_mov_b32_e32 v222, v220
	v_mov_b32_e32 v223, v97
	v_lshl_add_u64 v[222:223], v[218:219], 0, v[222:223]
	s_waitcnt lgkmcnt(7)
	global_store_dwordx4 v[222:223], v[186:189], off nt
	v_or_b32_e32 v222, 0x2000, v220
	v_mov_b32_e32 v223, v97
	v_lshl_add_u64 v[222:223], v[218:219], 0, v[222:223]
	s_waitcnt lgkmcnt(6)
	global_store_dwordx4 v[222:223], v[190:193], off nt
	v_or_b32_e32 v222, 0x4000, v220
	v_mov_b32_e32 v223, v97
	v_lshl_add_u64 v[222:223], v[218:219], 0, v[222:223]
	s_waitcnt lgkmcnt(5)
	global_store_dwordx4 v[222:223], v[194:197], off nt
	v_or_b32_e32 v222, 0x6000, v220
	v_mov_b32_e32 v223, v97
	v_lshl_add_u64 v[222:223], v[218:219], 0, v[222:223]
	s_waitcnt lgkmcnt(4)
	global_store_dwordx4 v[222:223], v[198:201], off nt
	v_or_b32_e32 v222, 0x8000, v220
	v_mov_b32_e32 v223, v97
	v_lshl_add_u64 v[222:223], v[218:219], 0, v[222:223]
	s_waitcnt lgkmcnt(3)
	global_store_dwordx4 v[222:223], v[202:205], off nt
	v_or_b32_e32 v222, 0xa000, v220
	v_mov_b32_e32 v223, v97
	v_lshl_add_u64 v[222:223], v[218:219], 0, v[222:223]
	s_waitcnt lgkmcnt(2)
	global_store_dwordx4 v[222:223], v[206:209], off nt
	v_or_b32_e32 v222, 0xc000, v220
	v_mov_b32_e32 v223, v97
	v_lshl_add_u64 v[222:223], v[218:219], 0, v[222:223]
	s_waitcnt lgkmcnt(1)
	global_store_dwordx4 v[222:223], v[210:213], off nt
	v_or_b32_e32 v222, 0xe000, v220
	v_mov_b32_e32 v223, v97
	v_lshl_add_u64 v[222:223], v[218:219], 0, v[222:223]
	s_waitcnt lgkmcnt(0)
	global_store_dwordx4 v[222:223], v[214:217], off nt
	s_branch .LBB0_275
.Lattn_epi_defer:
	s_waitcnt lgkmcnt(0)
	s_branch .LBB0_275
